# v28: out-projection sample-row tail: generic split-K tail GEMM reused with a 4-way split (was 16-way, K=128 slices) - 4x fewer scattered f32 atomics
# speedup vs baseline: 1.0333x; 1.0061x over previous
; template <int EPI>
; DI void gemm_epilogue(const Params& p, f32x4 (&acc)[8][4], int m0, int n0, int wr, int wc, int fr, int fq, u16* Cb, int ldc) {
;     ...
;         } else if (EPI == EPI_ATOM) {
; #pragma clang loop unroll(full)
;           for (int j = 0; j < 4; ++j) atomicAdd(p.out + O_Y + (size_t)row * 2048 + col + j, v[j]);
; __global__ void __launch_bounds__(NTHREADS) fwd_megakernel(Params p) {
;     ...
;   for (int id = bid; id < 128; id += nb) {
;     const int nt = id & 7, kc = id >> 3;
;     gemm_tile<EPI_ATOM>(p, p.GB + kc * 128, 2048, p.WT_OUT + kc * 128, 2048, 128, (MT / 256 - 1) * 256, nt * 256, smem, nullptr, 0);
;   }
.LBB0_1917:
	s_cmpk_gt_i32 s72, 0x1f
	s_cbranch_scc0 .LBB0_1919
	s_branch .LBB0_1925
.LBB0_1918:
	v_readlane_b32 s73, v231, 5
	s_cmpk_gt_i32 s72, 0x1f
	s_cbranch_scc1 .LBB0_1925
.LBB0_1919:
	s_mov_b32 s27, s72
	v_readlane_b32 s73, v231, 5
	v_readlane_b32 s18, v231, 36
	v_readlane_b32 s19, v231, 37
	v_readlane_b32 s20, v231, 22
	v_readlane_b32 s21, v231, 23
	s_waitcnt vmcnt(1)
	v_mov_b32_e32 v161, 0
	s_mov_b64 s[98:99], 0x4000000
	s_mov_b32 s6, 0x4000000
	s_mov_b32 s7, 0x4040000
	s_mov_b32 s8, 0x40000
	s_mov_b32 s9, 0x4080000
	s_mov_b32 s10, 0x80000
	s_mov_b32 s11, 0x40c0000
	s_mov_b32 s12, 0xc0000
	s_mov_b32 s5, 0
	s_branch .Lp6t_05
.Lp6t_04:
	s_waitcnt vmcnt(7)
	v_lshlrev_b32_e32 v121, 6, v160
	s_waitcnt vmcnt(6)
	v_lshl_or_b32 v126, v167, 7, v168
	v_lshlrev_b32_e32 v122, 2, v166
	v_add_u32_e32 v120, 0x4000, v126
	v_or3_b32 v122, v121, v122, s13
	v_ashrrev_i32_e32 v121, 31, v120
	v_lshlrev_b32_e32 v160, 2, v122
	v_add_u32_e32 v122, 0x4010, v126
	v_lshlrev_b64 v[120:121], 13, v[120:121]
	v_ashrrev_i32_e32 v123, 31, v122
	v_add_u32_e32 v124, 0x4020, v126
	v_lshl_add_u64 v[120:121], s[64:65], 0, v[120:121]
	v_lshlrev_b64 v[122:123], 13, v[122:123]
	v_ashrrev_i32_e32 v125, 31, v124
	v_lshl_add_u64 v[120:121], v[120:121], 0, v[160:161]
	v_lshl_add_u64 v[122:123], s[64:65], 0, v[122:123]
	v_lshlrev_b64 v[124:125], 13, v[124:125]
	global_atomic_add_f32 v[120:121], v156, off
	global_atomic_add_f32 v[120:121], v157, off offset:4
	global_atomic_add_f32 v[120:121], v158, off offset:8
	global_atomic_add_f32 v[120:121], v159, off offset:12
	v_lshl_add_u64 v[122:123], v[122:123], 0, v[160:161]
	v_lshl_add_u64 v[124:125], s[64:65], 0, v[124:125]
	global_atomic_add_f32 v[122:123], v140, off
	global_atomic_add_f32 v[122:123], v141, off offset:4
	global_atomic_add_f32 v[122:123], v142, off offset:8
	global_atomic_add_f32 v[122:123], v143, off offset:12
	v_lshl_add_u64 v[124:125], v[124:125], 0, v[160:161]
	global_atomic_add_f32 v[124:125], v116, off
	global_atomic_add_f32 v[124:125], v117, off offset:4
	global_atomic_add_f32 v[124:125], v118, off offset:8
	global_atomic_add_f32 v[124:125], v119, off offset:12
	v_add_u32_e32 v116, 0x4030, v126
	v_ashrrev_i32_e32 v117, 31, v116
	v_lshlrev_b64 v[116:117], 13, v[116:117]
	v_lshl_add_u64 v[116:117], s[64:65], 0, v[116:117]
	v_lshl_add_u64 v[116:117], v[116:117], 0, v[160:161]
	global_atomic_add_f32 v[116:117], v112, off
	global_atomic_add_f32 v[116:117], v113, off offset:4
	global_atomic_add_f32 v[116:117], v114, off offset:8
	global_atomic_add_f32 v[116:117], v115, off offset:12
	v_add_u32_e32 v112, 0x4040, v126
	v_ashrrev_i32_e32 v113, 31, v112
	v_lshlrev_b64 v[112:113], 13, v[112:113]
	v_lshl_add_u64 v[112:113], s[64:65], 0, v[112:113]
	v_lshl_add_u64 v[112:113], v[112:113], 0, v[160:161]
	global_atomic_add_f32 v[112:113], v100, off
	global_atomic_add_f32 v[112:113], v101, off offset:4
	global_atomic_add_f32 v[112:113], v102, off offset:8
	global_atomic_add_f32 v[112:113], v103, off offset:12
	v_add_u32_e32 v100, 0x4050, v126
	v_ashrrev_i32_e32 v101, 31, v100
	v_lshlrev_b64 v[100:101], 13, v[100:101]
	v_lshl_add_u64 v[100:101], s[64:65], 0, v[100:101]
	v_lshl_add_u64 v[100:101], v[100:101], 0, v[160:161]
	global_atomic_add_f32 v[100:101], v88, off
	global_atomic_add_f32 v[100:101], v89, off offset:4
	global_atomic_add_f32 v[100:101], v90, off offset:8
	global_atomic_add_f32 v[100:101], v91, off offset:12
	v_add_u32_e32 v88, 0x4060, v126
	v_ashrrev_i32_e32 v89, 31, v88
	v_lshlrev_b64 v[88:89], 13, v[88:89]
	v_lshl_add_u64 v[88:89], s[64:65], 0, v[88:89]
	v_lshl_add_u64 v[88:89], v[88:89], 0, v[160:161]
	global_atomic_add_f32 v[88:89], v68, off
	global_atomic_add_f32 v[88:89], v69, off offset:4
	global_atomic_add_f32 v[88:89], v70, off offset:8
	global_atomic_add_f32 v[88:89], v71, off offset:12
	v_add_u32_e32 v68, 0x4070, v126
	v_ashrrev_i32_e32 v69, 31, v68
	v_lshlrev_b64 v[68:69], 13, v[68:69]
	v_lshl_add_u64 v[68:69], s[64:65], 0, v[68:69]
	v_lshl_add_u64 v[68:69], v[68:69], 0, v[160:161]
	global_atomic_add_f32 v[68:69], v48, off
	global_atomic_add_f32 v[68:69], v49, off offset:4
	global_atomic_add_f32 v[68:69], v50, off offset:8
	global_atomic_add_f32 v[68:69], v51, off offset:12
	global_atomic_add_f32 v[120:121], v108, off offset:64
	global_atomic_add_f32 v[120:121], v109, off offset:68
	global_atomic_add_f32 v[120:121], v110, off offset:72
	global_atomic_add_f32 v[120:121], v111, off offset:76
	global_atomic_add_f32 v[122:123], v104, off offset:64
	global_atomic_add_f32 v[122:123], v105, off offset:68
	global_atomic_add_f32 v[122:123], v106, off offset:72
	global_atomic_add_f32 v[122:123], v107, off offset:76
	global_atomic_add_f32 v[124:125], v92, off offset:64
	global_atomic_add_f32 v[124:125], v93, off offset:68
	global_atomic_add_f32 v[124:125], v94, off offset:72
	global_atomic_add_f32 v[124:125], v95, off offset:76
	global_atomic_add_f32 v[116:117], v80, off offset:64
	global_atomic_add_f32 v[116:117], v81, off offset:68
	global_atomic_add_f32 v[116:117], v82, off offset:72
	global_atomic_add_f32 v[116:117], v83, off offset:76
	global_atomic_add_f32 v[112:113], v64, off offset:64
	global_atomic_add_f32 v[112:113], v65, off offset:68
	global_atomic_add_f32 v[112:113], v66, off offset:72
	global_atomic_add_f32 v[112:113], v67, off offset:76
	global_atomic_add_f32 v[100:101], v52, off offset:64
	global_atomic_add_f32 v[100:101], v53, off offset:68
	global_atomic_add_f32 v[100:101], v54, off offset:72
	global_atomic_add_f32 v[100:101], v55, off offset:76
	global_atomic_add_f32 v[88:89], v36, off offset:64
	global_atomic_add_f32 v[88:89], v37, off offset:68
	global_atomic_add_f32 v[88:89], v38, off offset:72
; template <int EPI>
; DI void gemm_epilogue(const Params& p, f32x4 (&acc)[8][4], int m0, int n0, int wr, int wc, int fr, int fq, u16* Cb, int ldc) {
;     ...
;         } else if (EPI == EPI_ATOM) {
; #pragma clang loop unroll(full)
;           for (int j = 0; j < 4; ++j) atomicAdd(p.out + O_Y + (size_t)row * 2048 + col + j, v[j]);
;         }
; template <int EPI>
; DI void gemm_tile(const Params& p, const u16* __restrict__ A, int lda, const u16* __restrict__ Bt, int ldb, int K, int m0, int n0,
;                   char* smem, u16* Cb, int ldc) {
;     ...
;   const int lr = tid >> 3, lk = (tid & 7) * 8;
;   const int lkw = ((tid & 7) ^ ((lr >> 1) & 7)) * 8;
;   const int fsw = (fr >> 1) & 7, fo0 = (fq ^ fsw) * 8, fo1 = ((4 + fq) ^ fsw) * 8;
;   const u16* Ag = A + (size_t)(m0 + lr) * lda + lk;
;   const u16* Bg = Bt + (size_t)(n0 + lr) * ldb + lk;
;   const int nk = K >> 6;
;   u32x4 ra[4], rb[4];
	global_atomic_add_f32 v[88:89], v39, off offset:76
	global_atomic_add_f32 v[68:69], v24, off offset:64
	global_atomic_add_f32 v[68:69], v25, off offset:68
	global_atomic_add_f32 v[68:69], v26, off offset:72
	global_atomic_add_f32 v[68:69], v27, off offset:76
	global_atomic_add_f32 v[120:121], v96, off offset:128
	global_atomic_add_f32 v[120:121], v97, off offset:132
	global_atomic_add_f32 v[120:121], v98, off offset:136
	global_atomic_add_f32 v[120:121], v99, off offset:140
	global_atomic_add_f32 v[122:123], v84, off offset:128
	global_atomic_add_f32 v[122:123], v85, off offset:132
	global_atomic_add_f32 v[122:123], v86, off offset:136
	global_atomic_add_f32 v[122:123], v87, off offset:140
	global_atomic_add_f32 v[124:125], v72, off offset:128
	global_atomic_add_f32 v[124:125], v73, off offset:132
	global_atomic_add_f32 v[124:125], v74, off offset:136
	global_atomic_add_f32 v[124:125], v75, off offset:140
	global_atomic_add_f32 v[116:117], v56, off offset:128
	global_atomic_add_f32 v[116:117], v57, off offset:132
	global_atomic_add_f32 v[116:117], v58, off offset:136
	global_atomic_add_f32 v[116:117], v59, off offset:140
	global_atomic_add_f32 v[112:113], v40, off offset:128
	global_atomic_add_f32 v[112:113], v41, off offset:132
	global_atomic_add_f32 v[112:113], v42, off offset:136
	global_atomic_add_f32 v[112:113], v43, off offset:140
	global_atomic_add_f32 v[100:101], v28, off offset:128
	global_atomic_add_f32 v[100:101], v29, off offset:132
	global_atomic_add_f32 v[100:101], v30, off offset:136
	global_atomic_add_f32 v[100:101], v31, off offset:140
	global_atomic_add_f32 v[88:89], v16, off offset:128
	global_atomic_add_f32 v[88:89], v17, off offset:132
	global_atomic_add_f32 v[88:89], v18, off offset:136
	global_atomic_add_f32 v[88:89], v19, off offset:140
	global_atomic_add_f32 v[68:69], v8, off offset:128
	global_atomic_add_f32 v[68:69], v9, off offset:132
	global_atomic_add_f32 v[68:69], v10, off offset:136
	global_atomic_add_f32 v[68:69], v11, off offset:140
	global_atomic_add_f32 v[120:121], v76, off offset:192
	global_atomic_add_f32 v[120:121], v77, off offset:196
	global_atomic_add_f32 v[120:121], v78, off offset:200
	global_atomic_add_f32 v[120:121], v79, off offset:204
	global_atomic_add_f32 v[122:123], v60, off offset:192
	global_atomic_add_f32 v[122:123], v61, off offset:196
	global_atomic_add_f32 v[122:123], v62, off offset:200
	global_atomic_add_f32 v[122:123], v63, off offset:204
	global_atomic_add_f32 v[124:125], v44, off offset:192
	global_atomic_add_f32 v[124:125], v45, off offset:196
	global_atomic_add_f32 v[124:125], v46, off offset:200
	global_atomic_add_f32 v[124:125], v47, off offset:204
	global_atomic_add_f32 v[116:117], v32, off offset:192
	global_atomic_add_f32 v[116:117], v33, off offset:196
	global_atomic_add_f32 v[116:117], v34, off offset:200
	global_atomic_add_f32 v[116:117], v35, off offset:204
	global_atomic_add_f32 v[112:113], v20, off offset:192
	global_atomic_add_f32 v[112:113], v21, off offset:196
	global_atomic_add_f32 v[112:113], v22, off offset:200
	global_atomic_add_f32 v[112:113], v23, off offset:204
	global_atomic_add_f32 v[100:101], v12, off offset:192
	global_atomic_add_f32 v[100:101], v13, off offset:196
	global_atomic_add_f32 v[100:101], v14, off offset:200
	global_atomic_add_f32 v[100:101], v15, off offset:204
	global_atomic_add_f32 v[88:89], v4, off offset:192
	global_atomic_add_f32 v[88:89], v5, off offset:196
	global_atomic_add_f32 v[88:89], v6, off offset:200
	global_atomic_add_f32 v[88:89], v7, off offset:204
	global_atomic_add_f32 v[68:69], v0, off offset:192
	global_atomic_add_f32 v[68:69], v1, off offset:196
	global_atomic_add_f32 v[68:69], v2, off offset:200
	global_atomic_add_f32 v[68:69], v3, off offset:204
	s_add_i32 s27, s27, s73
	s_cmpk_gt_i32 s27, 0x1f
	s_cbranch_scc1 .LBB0_1925
.Lp6t_05:
	s_lshl_b32 s0, s27, 6
	s_and_b32 s0, s0, 0xfffffe00
	s_ashr_i32 s1, s0, 31
	s_lshl_b64 s[0:1], s[0:1], 1
	s_add_u32 s14, s18, s0
	v_mov_b32_e32 v48, v194
	s_addc_u32 s15, s19, s1
	s_add_u32 s0, s20, s0
	v_ashrrev_i32_e32 v32, 3, v48
	v_ashrrev_i32_e32 v33, 31, v32
	s_addc_u32 s1, s21, s1
	s_lshl_b32 s4, s27, 8
	v_lshlrev_b64 v[0:1], 12, v[32:33]
	v_lshlrev_b32_e32 v2, 4, v48
	s_and_b32 s13, s4, 0x700
	v_lshl_add_u64 v[0:1], s[14:15], 0, v[0:1]
	v_and_b32_e32 v160, 0x70, v2
	v_lshl_add_u64 v[34:35], v[0:1], 0, v[160:161]
	v_add_u32_e32 v0, s13, v32
	v_ashrrev_i32_e32 v1, 31, v0
	v_add_co_u32_e32 v12, vcc, s6, v34
	v_lshlrev_b64 v[0:1], 12, v[0:1]
	s_nop 0
	v_addc_co_u32_e32 v13, vcc, 0, v35, vcc
	v_lshl_add_u64 v[0:1], s[0:1], 0, v[0:1]
	v_add_co_u32_e32 v36, vcc, s7, v34
	s_waitcnt vmcnt(0)
; DI int otid() { int t = threadIdx.x; asm volatile("" : "+v"(t)); return t; }
; #define G_LOAD(T) { const int k_ = (T) << 6; _Pragma("unroll") for (int i = 0; i < 4; ++i) { \
;     ra[i] = *(const u32x4*)(Ag + (size_t)(i * 64) * lda + k_); rb[i] = *(const u32x4*)(Bg + (size_t)(i * 64) * ldb + k_); } }
; #define L_STORE(ST) { u16* dA_ = sbase + (ST) * GSTAGE + lr * LSTR + lkw; u16* dB_ = dA_ + 256 * LSTR; _Pragma("unroll") for (int i = 0; i < 4; ++i) { \
;     *(u32x4*)(dA_ + i * 64 * LSTR) = ra[i]; *(u32x4*)(dB_ + i * 64 * LSTR) = rb[i]; } }
; template <int EPI>
; DI void gemm_tile(const Params& p, const u16* __restrict__ A, int lda, const u16* __restrict__ Bt, int ldb, int K, int m0, int n0,
;                   char* smem, u16* Cb, int ldc) {
;     ...
;   const int tid = otid(), lane = tid & 63, w = tid >> 6;
;   const int wr = w >> 2, wc = w & 3, fr = lane & 15, fq = lane >> 4;
;   f32x4 acc[8][4];
; #pragma unroll
;   for (int m = 0; m < 8; ++m)
; #pragma unroll
;     for (int n = 0; n < 4; ++n) acc[m][n] = (f32x4){0.f, 0.f, 0.f, 0.f};
;   const int lr = tid >> 3, lk = (tid & 7) * 8;
;   const int lkw = ((tid & 7) ^ ((lr >> 1) & 7)) * 8;
;   const int fsw = (fr >> 1) & 7, fo0 = (fq ^ fsw) * 8, fo1 = ((4 + fq) ^ fsw) * 8;
;   const u16* Ag = A + (size_t)(m0 + lr) * lda + lk;
;   const u16* Bg = Bt + (size_t)(n0 + lr) * ldb + lk;
;   const int nk = K >> 6;
;   u32x4 ra[4], rb[4];
;     ...
;   G_LOAD(0)
;   L_STORE(0)
;   G_LOAD(1)
	v_lshl_add_u64 v[162:163], v[0:1], 0, v[160:161]
	v_addc_co_u32_e32 v37, vcc, 0, v35, vcc
	v_add_co_u32_e32 v38, vcc, s8, v162
	global_load_dwordx4 v[0:3], v[162:163], off
	s_nop 0
	v_addc_co_u32_e32 v39, vcc, 0, v163, vcc
	v_add_co_u32_e32 v40, vcc, s9, v34
	global_load_dwordx4 v[4:7], v[12:13], off
	global_load_dwordx4 v[8:11], v[36:37], off
	v_addc_co_u32_e32 v41, vcc, 0, v35, vcc
	v_add_co_u32_e32 v42, vcc, s10, v162
	global_load_dwordx4 v[12:15], v[38:39], off
	s_nop 0
	v_addc_co_u32_e32 v43, vcc, 0, v163, vcc
	v_add_co_u32_e32 v44, vcc, s11, v34
	global_load_dwordx4 v[16:19], v[40:41], off
	s_nop 0
	v_addc_co_u32_e32 v45, vcc, 0, v35, vcc
	v_add_co_u32_e32 v46, vcc, s12, v162
	global_load_dwordx4 v[20:23], v[42:43], off
	s_nop 0
	v_addc_co_u32_e32 v47, vcc, 0, v163, vcc
	global_load_dwordx4 v[24:27], v[44:45], off
	global_load_dwordx4 v[28:31], v[46:47], off
	v_lshl_add_u64 v[164:165], v[34:35], 0, s[98:99]
	global_load_dwordx4 v[144:147], v[44:45], off offset:128
	global_load_dwordx4 v[132:135], v[40:41], off offset:128
	global_load_dwordx4 v[128:131], v[36:37], off offset:128
	global_load_dwordx4 v[120:123], v[164:165], off offset:128
	global_load_dwordx4 v[124:127], v[162:163], off offset:128
	global_load_dwordx4 v[152:155], v[46:47], off offset:128
	global_load_dwordx4 v[148:151], v[42:43], off offset:128
	global_load_dwordx4 v[136:139], v[38:39], off offset:128
	v_lshrrev_b32_e32 v33, 4, v48
	v_bfe_u32 v160, v48, 6, 2
	v_ashrrev_i32_e32 v167, 8, v48
	v_bfe_u32 v166, v48, 4, 2
	v_bfe_u32 v49, v48, 1, 3
	v_and_b32_e32 v168, 15, v48
	v_xor_b32_e32 v48, v33, v48
	v_lshlrev_b32_e32 v48, 4, v48
	v_bitop3_b32 v33, v33, v49, 3 bitop3:0x6c
	v_bitop3_b32 v49, v166, v49, 4 bitop3:0x36
	v_lshlrev_b32_e32 v32, 7, v32
	v_and_b32_e32 v48, 0x70, v48
	v_lshlrev_b32_e32 v50, 6, v168
	v_lshlrev_b32_e32 v49, 3, v49
	v_lshlrev_b32_e32 v33, 3, v33
	v_add3_u32 v172, 0, v32, v48
	v_lshlrev_b32_e32 v169, 14, v167
	v_lshlrev_b32_e32 v170, 13, v160
	v_lshlrev_b32_e32 v171, 1, v50
	v_lshlrev_b32_e32 v173, 1, v33
	v_lshlrev_b32_e32 v174, 1, v49
	s_mov_b32 s14, s5
	s_mov_b32 s15, s5
	v_mov_b32_e32 v48, 0
	v_mov_b32_e32 v49, v161
	v_mov_b32_e32 v50, v161
	v_mov_b32_e32 v51, v161
	v_mov_b32_e32 v36, 0
	v_mov_b32_e32 v37, v161
	v_mov_b32_e32 v38, v161
	v_mov_b32_e32 v39, v161
	v_mov_b32_e32 v68, 0
	v_mov_b32_e32 v69, v161
	v_mov_b32_e32 v70, v161
	v_mov_b32_e32 v71, v161
	v_mov_b32_e32 v52, 0
	v_mov_b32_e32 v53, v161
	v_mov_b32_e32 v54, v161
	s_waitcnt vmcnt(14)
	ds_write_b128 v172, v[4:7]
	s_waitcnt vmcnt(13)
	ds_write_b128 v172, v[8:11] offset:8192
	s_waitcnt vmcnt(11)
	ds_write_b128 v172, v[16:19] offset:16384
	s_waitcnt vmcnt(9)
	ds_write_b128 v172, v[24:27] offset:24576
	ds_write_b128 v172, v[0:3] offset:32768
	ds_write_b128 v172, v[12:15] offset:40960
	ds_write_b128 v172, v[20:23] offset:49152
	s_waitcnt vmcnt(8)
	ds_write_b128 v172, v[28:31] offset:57344
	v_mov_b32_e32 v0, 0
	v_mov_b32_e32 v1, v161
	v_mov_b32_e32 v2, v161
	v_mov_b32_e32 v3, v161
	v_mov_b32_e32 v8, 0
	v_mov_b32_e32 v9, v161
	v_mov_b32_e32 v10, v161
	v_mov_b32_e32 v11, v161
	v_mov_b32_e32 v24, 0
	v_mov_b32_e32 v25, v161
	v_mov_b32_e32 v26, v161
	v_mov_b32_e32 v27, v161
	v_mov_b32_e32 v4, 0
	v_mov_b32_e32 v5, v161
	v_mov_b32_e32 v6, v161
	v_mov_b32_e32 v7, v161
	v_mov_b32_e32 v16, 0
	v_mov_b32_e32 v17, v161
	v_mov_b32_e32 v18, v161
	v_mov_b32_e32 v19, v161
	v_mov_b32_e32 v12, 0
	v_mov_b32_e32 v13, v161
	v_mov_b32_e32 v14, v161
	v_mov_b32_e32 v15, v161
	v_mov_b32_e32 v28, 0
	v_mov_b32_e32 v29, v161
	v_mov_b32_e32 v30, v161
	v_mov_b32_e32 v31, v161
	v_mov_b32_e32 v55, v161
	v_mov_b32_e32 v88, 0
	v_mov_b32_e32 v89, v161
	v_mov_b32_e32 v90, v161
	v_mov_b32_e32 v91, v161
	v_mov_b32_e32 v20, 0
	v_mov_b32_e32 v21, v161
	v_mov_b32_e32 v22, v161
	v_mov_b32_e32 v23, v161
	v_mov_b32_e32 v40, 0
	v_mov_b32_e32 v41, v161
	v_mov_b32_e32 v42, v161
	v_mov_b32_e32 v43, v161
	v_mov_b32_e32 v64, 0
	v_mov_b32_e32 v65, v161
	v_mov_b32_e32 v66, v161
	v_mov_b32_e32 v67, v161
	v_mov_b32_e32 v100, 0
	v_mov_b32_e32 v101, v161
	v_mov_b32_e32 v102, v161
	v_mov_b32_e32 v103, v161
	v_mov_b32_e32 v32, 0
	v_mov_b32_e32 v33, v161
	v_mov_b32_e32 v34, v161
	v_mov_b32_e32 v35, v161
	v_mov_b32_e32 v56, 0
	v_mov_b32_e32 v57, v161
	v_mov_b32_e32 v58, v161
	v_mov_b32_e32 v59, v161
	v_mov_b32_e32 v80, 0
	v_mov_b32_e32 v81, v161
	v_mov_b32_e32 v82, v161
	v_mov_b32_e32 v83, v161
	v_mov_b32_e32 v112, 0
	v_mov_b32_e32 v113, v161
	v_mov_b32_e32 v114, v161
	v_mov_b32_e32 v115, v161
	v_mov_b32_e32 v44, 0
	v_mov_b32_e32 v45, v161
	v_mov_b32_e32 v46, v161
	v_mov_b32_e32 v47, v161
	v_mov_b32_e32 v72, 0
	v_mov_b32_e32 v73, v161
	v_mov_b32_e32 v74, v161
	v_mov_b32_e32 v75, v161
	v_mov_b32_e32 v92, 0
	v_mov_b32_e32 v93, v161
	v_mov_b32_e32 v94, v161
	v_mov_b32_e32 v95, v161
	v_mov_b32_e32 v116, 0
	v_mov_b32_e32 v117, v161
	v_mov_b32_e32 v118, v161
	v_mov_b32_e32 v119, v161
	v_mov_b32_e32 v60, 0
	v_mov_b32_e32 v61, v161
	v_mov_b32_e32 v62, v161
	v_mov_b32_e32 v63, v161
	v_mov_b32_e32 v84, 0
	v_mov_b32_e32 v85, v161
	v_mov_b32_e32 v86, v161
	v_mov_b32_e32 v87, v161
	v_mov_b32_e32 v104, 0
	v_mov_b32_e32 v105, v161
	v_mov_b32_e32 v106, v161
	v_mov_b32_e32 v107, v161
	v_mov_b32_e32 v140, 0
	v_mov_b32_e32 v141, v161
	v_mov_b32_e32 v142, v161
	v_mov_b32_e32 v143, v161
	v_mov_b32_e32 v76, 0
	v_mov_b32_e32 v77, v161
	v_mov_b32_e32 v78, v161
	v_mov_b32_e32 v79, v161
	v_mov_b32_e32 v96, 0
	v_mov_b32_e32 v97, v161
	v_mov_b32_e32 v98, v161
	v_mov_b32_e32 v99, v161
	v_mov_b32_e32 v108, 0
	v_mov_b32_e32 v109, v161
	v_mov_b32_e32 v110, v161
	v_mov_b32_e32 v111, v161
	v_mov_b32_e32 v156, 0
	v_mov_b32_e32 v157, v161
	v_mov_b32_e32 v158, v161
	v_mov_b32_e32 v159, v161
	s_branch .Lp6t_07
; #define G_LOAD(T) { const int k_ = (T) << 6; _Pragma("unroll") for (int i = 0; i < 4; ++i) { \
;     ra[i] = *(const u32x4*)(Ag + (size_t)(i * 64) * lda + k_); rb[i] = *(const u32x4*)(Bg + (size_t)(i * 64) * ldb + k_); } }
; #define L_STORE(ST) { u16* dA_ = sbase + (ST) * GSTAGE + lr * LSTR + lkw; u16* dB_ = dA_ + 256 * LSTR; _Pragma("unroll") for (int i = 0; i < 4; ++i) { \
;     *(u32x4*)(dA_ + i * 64 * LSTR) = ra[i]; *(u32x4*)(dB_ + i * 64 * LSTR) = rb[i]; } }
; template <int EPI>
; DI void gemm_tile(const Params& p, const u16* __restrict__ A, int lda, const u16* __restrict__ Bt, int ldb, int K, int m0, int n0,
;                   char* smem, u16* Cb, int ldc) {
;     ...
;   for (int kt = 0; kt < nk; ++kt) {
;     __syncthreads();
;     if (kt + 1 < nk) L_STORE((kt + 1) & 1)
;     G_LOAD(min(kt + 2, nk - 1))
;     const u16* cA = sbase + (kt & 1) * GSTAGE + (wr * 128 + fr) * LSTR;
;     const u16* cB = sbase + (kt & 1) * GSTAGE + 256 * LSTR + (wc * 64 + fr) * LSTR;
; #pragma unroll
;     for (int ks = 0; ks < 2; ++ks) {
;       bf16x8 bfr[4];
; #pragma unroll
;       for (int n = 0; n < 4; ++n) bfr[n] = *(const bf16x8*)(cB + n * 16 * LSTR + (ks ? fo1 : fo0));
; #pragma unroll
;       for (int mh = 0; mh < 2; ++mh) {
;         bf16x8 af[4];
; #pragma unroll
;         for (int m = 0; m < 4; ++m) af[m] = *(const bf16x8*)(cA + (mh * 4 + m) * 16 * LSTR + (ks ? fo1 : fo0));
;         __builtin_amdgcn_s_setprio(1);
; #pragma unroll
;         for (int m = 0; m < 4; ++m)
; #pragma unroll
;           for (int n = 0; n < 4; ++n)
;             acc[mh * 4 + m][n] = EpiSwap<EPI>::v ? __builtin_amdgcn_mfma_f32_16x16x32_bf16(bfr[n], af[m], acc[mh * 4 + m][n], 0, 0, 0)
;                                                  : __builtin_amdgcn_mfma_f32_16x16x32_bf16(af[m], bfr[n], acc[mh * 4 + m][n], 0, 0, 0);
;         __builtin_amdgcn_s_setprio(0);
;       }
.Lp6t_06:
	s_min_i32 s0, s15, 5
	s_lshl_b32 s4, s0, 7
	s_waitcnt vmcnt(0)
	v_lshl_add_u64 v[144:145], v[164:165], 0, s[4:5]
	s_waitcnt vmcnt(5)
	v_add_co_u32_e32 v128, vcc, s8, v144
	s_waitcnt vmcnt(2)
	v_lshl_add_u64 v[152:153], v[162:163], 0, s[4:5]
	v_addc_co_u32_e32 v129, vcc, 0, v145, vcc
	v_add_co_u32_e32 v132, vcc, s8, v152
	global_load_dwordx4 v[120:123], v[144:145], off offset:256
	global_load_dwordx4 v[124:127], v[152:153], off offset:256
	v_addc_co_u32_e32 v133, vcc, 0, v153, vcc
	global_load_dwordx4 v[136:139], v[132:133], off offset:256
	v_add_co_u32_e32 v132, vcc, s10, v144
	global_load_dwordx4 v[128:131], v[128:129], off offset:256
	s_nop 0
	v_addc_co_u32_e32 v133, vcc, 0, v145, vcc
	v_add_co_u32_e32 v146, vcc, s10, v152
	global_load_dwordx4 v[132:135], v[132:133], off offset:256
	s_nop 0
	v_addc_co_u32_e32 v147, vcc, 0, v153, vcc
	v_add_co_u32_e32 v144, vcc, s12, v144
	global_load_dwordx4 v[148:151], v[146:147], off offset:256
	s_nop 0
	v_addc_co_u32_e32 v145, vcc, 0, v145, vcc
	v_add_co_u32_e32 v152, vcc, s12, v152
	s_and_b32 s0, s14, 0x8000
	s_nop 0
	v_addc_co_u32_e32 v153, vcc, 0, v153, vcc
	global_load_dwordx4 v[152:155], v[152:153], off offset:256
	s_lshl_b32 s0, s0, 1
	global_load_dwordx4 v[144:147], v[144:145], off offset:256
	s_add_i32 s0, s0, 0
	v_add3_u32 v175, s0, v169, v171
	v_add3_u32 v192, s0, v170, v171
	v_add_u32_e32 v188, v192, v173
	v_add_u32_e32 v193, v175, v173
	ds_read_b128 v[176:179], v188 offset:32768
	ds_read_b128 v[180:183], v188 offset:34816
	ds_read_b128 v[184:187], v188 offset:36864
	ds_read_b128 v[188:191], v188 offset:38912
	ds_read_b128 v[196:199], v193
	ds_read_b128 v[200:203], v193 offset:2048
	ds_read_b128 v[204:207], v193 offset:4096
	ds_read_b128 v[208:211], v193 offset:6144
	s_add_i32 s15, s15, 1
	s_setprio 1
	s_waitcnt lgkmcnt(3)
	v_mfma_f32_16x16x32_bf16 v[156:159], v[176:179], v[196:199], v[156:159]
	v_mfma_f32_16x16x32_bf16 v[108:111], v[180:183], v[196:199], v[108:111]
	v_mfma_f32_16x16x32_bf16 v[96:99], v[184:187], v[196:199], v[96:99]
	v_mfma_f32_16x16x32_bf16 v[76:79], v[188:191], v[196:199], v[76:79]
	s_waitcnt lgkmcnt(2)
	v_mfma_f32_16x16x32_bf16 v[140:143], v[176:179], v[200:203], v[140:143]
	v_mfma_f32_16x16x32_bf16 v[104:107], v[180:183], v[200:203], v[104:107]
	v_mfma_f32_16x16x32_bf16 v[84:87], v[184:187], v[200:203], v[84:87]
	v_mfma_f32_16x16x32_bf16 v[60:63], v[188:191], v[200:203], v[60:63]
	s_waitcnt lgkmcnt(1)
	v_mfma_f32_16x16x32_bf16 v[116:119], v[176:179], v[204:207], v[116:119]
	v_mfma_f32_16x16x32_bf16 v[92:95], v[180:183], v[204:207], v[92:95]
	v_mfma_f32_16x16x32_bf16 v[72:75], v[184:187], v[204:207], v[72:75]
	v_mfma_f32_16x16x32_bf16 v[44:47], v[188:191], v[204:207], v[44:47]
	s_waitcnt lgkmcnt(0)
	v_mfma_f32_16x16x32_bf16 v[112:115], v[176:179], v[208:211], v[112:115]
	v_mfma_f32_16x16x32_bf16 v[80:83], v[180:183], v[208:211], v[80:83]
	v_mfma_f32_16x16x32_bf16 v[56:59], v[184:187], v[208:211], v[56:59]
	v_mfma_f32_16x16x32_bf16 v[32:35], v[188:191], v[208:211], v[32:35]
	s_setprio 0
	ds_read_b128 v[196:199], v193 offset:8192
	ds_read_b128 v[200:203], v193 offset:10240
	ds_read_b128 v[204:207], v193 offset:12288
	ds_read_b128 v[208:211], v193 offset:14336
	s_setprio 1
	s_waitcnt lgkmcnt(3)
	v_mfma_f32_16x16x32_bf16 v[100:103], v[176:179], v[196:199], v[100:103]
	v_mfma_f32_16x16x32_bf16 v[64:67], v[180:183], v[196:199], v[64:67]
	v_mfma_f32_16x16x32_bf16 v[40:43], v[184:187], v[196:199], v[40:43]
	v_mfma_f32_16x16x32_bf16 v[20:23], v[188:191], v[196:199], v[20:23]
	s_waitcnt lgkmcnt(2)
	v_mfma_f32_16x16x32_bf16 v[88:91], v[176:179], v[200:203], v[88:91]
	v_mfma_f32_16x16x32_bf16 v[52:55], v[180:183], v[200:203], v[52:55]
	v_mfma_f32_16x16x32_bf16 v[28:31], v[184:187], v[200:203], v[28:31]
	v_mfma_f32_16x16x32_bf16 v[12:15], v[188:191], v[200:203], v[12:15]
	s_waitcnt lgkmcnt(1)
	v_mfma_f32_16x16x32_bf16 v[68:71], v[176:179], v[204:207], v[68:71]
	v_mfma_f32_16x16x32_bf16 v[36:39], v[180:183], v[204:207], v[36:39]
	v_mfma_f32_16x16x32_bf16 v[16:19], v[184:187], v[204:207], v[16:19]
	v_mfma_f32_16x16x32_bf16 v[4:7], v[188:191], v[204:207], v[4:7]
	s_waitcnt lgkmcnt(0)
; #define G_LOAD(T) { const int k_ = (T) << 6; _Pragma("unroll") for (int i = 0; i < 4; ++i) { \
;     ra[i] = *(const u32x4*)(Ag + (size_t)(i * 64) * lda + k_); rb[i] = *(const u32x4*)(Bg + (size_t)(i * 64) * ldb + k_); } }
; #define L_STORE(ST) { u16* dA_ = sbase + (ST) * GSTAGE + lr * LSTR + lkw; u16* dB_ = dA_ + 256 * LSTR; _Pragma("unroll") for (int i = 0; i < 4; ++i) { \
;     *(u32x4*)(dA_ + i * 64 * LSTR) = ra[i]; *(u32x4*)(dB_ + i * 64 * LSTR) = rb[i]; } }
; template <int EPI>
; DI void gemm_tile(const Params& p, const u16* __restrict__ A, int lda, const u16* __restrict__ Bt, int ldb, int K, int m0, int n0,
;                   char* smem, u16* Cb, int ldc) {
;     ...
;   for (int kt = 0; kt < nk; ++kt) {
;     __syncthreads();
;     if (kt + 1 < nk) L_STORE((kt + 1) & 1)
;     G_LOAD(min(kt + 2, nk - 1))
;     const u16* cA = sbase + (kt & 1) * GSTAGE + (wr * 128 + fr) * LSTR;
;     const u16* cB = sbase + (kt & 1) * GSTAGE + 256 * LSTR + (wc * 64 + fr) * LSTR;
; #pragma unroll
;     for (int ks = 0; ks < 2; ++ks) {
;       bf16x8 bfr[4];
; #pragma unroll
;       for (int n = 0; n < 4; ++n) bfr[n] = *(const bf16x8*)(cB + n * 16 * LSTR + (ks ? fo1 : fo0));
; #pragma unroll
;       for (int mh = 0; mh < 2; ++mh) {
;         bf16x8 af[4];
; #pragma unroll
;         for (int m = 0; m < 4; ++m) af[m] = *(const bf16x8*)(cA + (mh * 4 + m) * 16 * LSTR + (ks ? fo1 : fo0));
;         __builtin_amdgcn_s_setprio(1);
; #pragma unroll
;         for (int m = 0; m < 4; ++m)
; #pragma unroll
;           for (int n = 0; n < 4; ++n)
;             acc[mh * 4 + m][n] = EpiSwap<EPI>::v ? __builtin_amdgcn_mfma_f32_16x16x32_bf16(bfr[n], af[m], acc[mh * 4 + m][n], 0, 0, 0)
;                                                  : __builtin_amdgcn_mfma_f32_16x16x32_bf16(af[m], bfr[n], acc[mh * 4 + m][n], 0, 0, 0);
;         __builtin_amdgcn_s_setprio(0);
;       }
;     }
;   }
	v_mfma_f32_16x16x32_bf16 v[48:51], v[176:179], v[208:211], v[48:51]
	v_mfma_f32_16x16x32_bf16 v[24:27], v[180:183], v[208:211], v[24:27]
	v_mfma_f32_16x16x32_bf16 v[8:11], v[184:187], v[208:211], v[8:11]
	v_mfma_f32_16x16x32_bf16 v[0:3], v[188:191], v[208:211], v[0:3]
	s_setprio 0
	v_add_u32_e32 v188, v192, v174
	v_add_u32_e32 v175, v175, v174
	ds_read_b128 v[176:179], v188 offset:32768
	ds_read_b128 v[180:183], v188 offset:34816
	ds_read_b128 v[184:187], v188 offset:36864
	ds_read_b128 v[188:191], v188 offset:38912
	ds_read_b128 v[196:199], v175
	ds_read_b128 v[200:203], v175 offset:2048
	ds_read_b128 v[204:207], v175 offset:4096
	ds_read_b128 v[208:211], v175 offset:6144
	s_setprio 1
	s_waitcnt lgkmcnt(3)
	v_mfma_f32_16x16x32_bf16 v[156:159], v[176:179], v[196:199], v[156:159]
	v_mfma_f32_16x16x32_bf16 v[108:111], v[180:183], v[196:199], v[108:111]
	v_mfma_f32_16x16x32_bf16 v[96:99], v[184:187], v[196:199], v[96:99]
	v_mfma_f32_16x16x32_bf16 v[76:79], v[188:191], v[196:199], v[76:79]
	s_waitcnt lgkmcnt(2)
	v_mfma_f32_16x16x32_bf16 v[140:143], v[176:179], v[200:203], v[140:143]
	v_mfma_f32_16x16x32_bf16 v[104:107], v[180:183], v[200:203], v[104:107]
	v_mfma_f32_16x16x32_bf16 v[84:87], v[184:187], v[200:203], v[84:87]
	v_mfma_f32_16x16x32_bf16 v[60:63], v[188:191], v[200:203], v[60:63]
	s_waitcnt lgkmcnt(1)
	v_mfma_f32_16x16x32_bf16 v[116:119], v[176:179], v[204:207], v[116:119]
	v_mfma_f32_16x16x32_bf16 v[92:95], v[180:183], v[204:207], v[92:95]
	v_mfma_f32_16x16x32_bf16 v[72:75], v[184:187], v[204:207], v[72:75]
	v_mfma_f32_16x16x32_bf16 v[44:47], v[188:191], v[204:207], v[44:47]
	s_waitcnt lgkmcnt(0)
	v_mfma_f32_16x16x32_bf16 v[112:115], v[176:179], v[208:211], v[112:115]
	v_mfma_f32_16x16x32_bf16 v[80:83], v[180:183], v[208:211], v[80:83]
	v_mfma_f32_16x16x32_bf16 v[56:59], v[184:187], v[208:211], v[56:59]
	v_mfma_f32_16x16x32_bf16 v[32:35], v[188:191], v[208:211], v[32:35]
	s_setprio 0
	ds_read_b128 v[196:199], v175 offset:8192
	ds_read_b128 v[200:203], v175 offset:10240
	ds_read_b128 v[204:207], v175 offset:12288
	ds_read_b128 v[208:211], v175 offset:14336
	s_setprio 1
	s_waitcnt lgkmcnt(3)
	v_mfma_f32_16x16x32_bf16 v[100:103], v[176:179], v[196:199], v[100:103]
	v_mfma_f32_16x16x32_bf16 v[64:67], v[180:183], v[196:199], v[64:67]
	v_mfma_f32_16x16x32_bf16 v[40:43], v[184:187], v[196:199], v[40:43]
	v_mfma_f32_16x16x32_bf16 v[20:23], v[188:191], v[196:199], v[20:23]
	s_waitcnt lgkmcnt(2)
	v_mfma_f32_16x16x32_bf16 v[88:91], v[176:179], v[200:203], v[88:91]
	v_mfma_f32_16x16x32_bf16 v[52:55], v[180:183], v[200:203], v[52:55]
	v_mfma_f32_16x16x32_bf16 v[28:31], v[184:187], v[200:203], v[28:31]
	v_mfma_f32_16x16x32_bf16 v[12:15], v[188:191], v[200:203], v[12:15]
	s_waitcnt lgkmcnt(1)
	v_mfma_f32_16x16x32_bf16 v[68:71], v[176:179], v[204:207], v[68:71]
	v_mfma_f32_16x16x32_bf16 v[36:39], v[180:183], v[204:207], v[36:39]
	v_mfma_f32_16x16x32_bf16 v[16:19], v[184:187], v[204:207], v[16:19]
	v_mfma_f32_16x16x32_bf16 v[4:7], v[188:191], v[204:207], v[4:7]
	s_waitcnt lgkmcnt(0)
	v_mfma_f32_16x16x32_bf16 v[48:51], v[176:179], v[208:211], v[48:51]
	v_mfma_f32_16x16x32_bf16 v[24:27], v[180:183], v[208:211], v[24:27]
	v_mfma_f32_16x16x32_bf16 v[8:11], v[184:187], v[208:211], v[8:11]
	v_mfma_f32_16x16x32_bf16 v[0:3], v[188:191], v[208:211], v[0:3]
	s_setprio 0
	s_cmp_lg_u32 s15, 8
	s_mov_b32 s14, s16
	s_cbranch_scc0 .Lp6t_04
.Lp6t_07:
	s_cmp_lt_u32 s15, 7
	s_mov_b64 s[0:1], -1
	s_waitcnt lgkmcnt(0)
	s_barrier
	s_cbranch_scc1 .Lp6t_09
	s_add_i32 s16, s14, 0x8000
	s_mov_b64 s[0:1], 0
.Lp6t_09:
	s_andn2_b64 vcc, exec, s[0:1]
	s_cbranch_vccnz .Lp6t_06
	s_add_i32 s16, s14, 0x8000
	s_and_b32 s0, s16, 0x8000
	v_lshl_add_u32 v175, s0, 1, v172
	s_waitcnt vmcnt(4)
	ds_write_b128 v175, v[120:123]
	s_waitcnt vmcnt(3)
	ds_write_b128 v175, v[124:127] offset:32768
	ds_write_b128 v175, v[128:131] offset:8192
	s_waitcnt vmcnt(0)
	ds_write_b128 v175, v[136:139] offset:40960
	ds_write_b128 v175, v[132:135] offset:16384
	ds_write_b128 v175, v[148:151] offset:49152
	ds_write_b128 v175, v[144:147] offset:24576
	ds_write_b128 v175, v[152:155] offset:57344
	s_branch .Lp6t_06
.LBB0_1925:
	s_waitcnt vmcnt(63) expcnt(7) lgkmcnt(15)
	s_barrier
	s_and_saveexec_b64 s[0:1], s[96:97]
	v_readlane_b32 s18, v231, 2
	v_readlane_b32 s19, v231, 3
	s_cbranch_execz .LBB0_1935
	v_readlane_b32 s4, v231, 0
	v_readlane_b32 s5, v231, 1
	buffer_wbl2 sc1
	s_waitcnt vmcnt(0)
	s_load_dwordx2 s[4:5], s[4:5], 0x58
	v_mov_b32_e32 v2, 0
	s_mov_b64 s[6:7], exec
	v_mbcnt_lo_u32_b32 v1, s6, 0
	v_mbcnt_hi_u32_b32 v1, s7, v1
	s_waitcnt lgkmcnt(0)
	global_load_dword v0, v2, s[4:5] offset:40
	v_cmp_eq_u32_e32 vcc, 0, v1
	s_and_saveexec_b64 s[8:9], vcc
	s_cbranch_execz .LBB0_1928
	s_bcnt1_i32_b64 s6, s[6:7]
	v_mov_b32_e32 v3, s6
	global_atomic_add v3, v2, v3, s[4:5] offset:32 sc0

; __global__ void __launch_bounds__(NTHREADS) fwd_megakernel(Params p) {
;   extern __shared__ __attribute__((aligned(16))) char smem[];
;   cg::grid_group grid = cg::this_grid();
	.amdhsa_kernel _Z14fwd_megakernel6Params
		.amdhsa_group_segment_fixed_size 0
		.amdhsa_private_segment_fixed_size 0
		.amdhsa_kernarg_size 648
		.amdhsa_user_sgpr_count 2
		.amdhsa_user_sgpr_dispatch_ptr 0
		.amdhsa_user_sgpr_queue_ptr 0
		.amdhsa_user_sgpr_kernarg_segment_ptr 1
		.amdhsa_user_sgpr_dispatch_id 0
		.amdhsa_user_sgpr_kernarg_preload_length 0
		.amdhsa_user_sgpr_kernarg_preload_offset 0
		.amdhsa_user_sgpr_private_segment_size 0
		.amdhsa_uses_dynamic_stack 0
		.amdhsa_enable_private_segment 0
		.amdhsa_system_sgpr_workgroup_id_x 1
		.amdhsa_system_sgpr_workgroup_id_y 0
		.amdhsa_system_sgpr_workgroup_id_z 0
		.amdhsa_system_sgpr_workgroup_info 0
		.amdhsa_system_vgpr_workitem_id 2
		.amdhsa_next_free_vgpr 256
		.amdhsa_next_free_sgpr 100
		.amdhsa_accum_offset 256
		.amdhsa_reserve_vcc 1
		.amdhsa_float_round_mode_32 0
		.amdhsa_float_round_mode_16_64 0
		.amdhsa_float_denorm_mode_32 3
		.amdhsa_float_denorm_mode_16_64 3
		.amdhsa_dx10_clamp 1
		.amdhsa_ieee_mode 1
		.amdhsa_fp16_overflow 0
		.amdhsa_tg_split 0
		.amdhsa_exception_fp_ieee_invalid_op 0
		.amdhsa_exception_fp_denorm_src 0
		.amdhsa_exception_fp_ieee_div_zero 0
		.amdhsa_exception_fp_ieee_overflow 0
		.amdhsa_exception_fp_ieee_underflow 0
		.amdhsa_exception_fp_ieee_inexact 0
		.amdhsa_exception_int_div_zero 0
	.end_amdhsa_kernel

; __global__ void __launch_bounds__(NTHREADS) fwd_megakernel(Params p) {
;   extern __shared__ __attribute__((aligned(16))) char smem[];
;   cg::grid_group grid = cg::this_grid();
amdhsa.kernels:
  - .agpr_count:     0
    .args:
      - .offset:         0
        .size:           392
        .value_kind:     by_value
      - .offset:         392
        .size:           4
        .value_kind:     hidden_block_count_x
      - .offset:         396
        .size:           4
        .value_kind:     hidden_block_count_y
      - .offset:         400
        .size:           4
        .value_kind:     hidden_block_count_z
      - .offset:         404
        .size:           2
        .value_kind:     hidden_group_size_x
      - .offset:         406
        .size:           2
        .value_kind:     hidden_group_size_y
      - .offset:         408
        .size:           2
        .value_kind:     hidden_group_size_z
      - .offset:         410
        .size:           2
        .value_kind:     hidden_remainder_x
      - .offset:         412
        .size:           2
        .value_kind:     hidden_remainder_y
      - .offset:         414
        .size:           2
        .value_kind:     hidden_remainder_z
      - .offset:         432
        .size:           8
        .value_kind:     hidden_global_offset_x
      - .offset:         440
        .size:           8
        .value_kind:     hidden_global_offset_y
      - .offset:         448
        .size:           8
        .value_kind:     hidden_global_offset_z
      - .offset:         456
        .size:           2
        .value_kind:     hidden_grid_dims
      - .offset:         480
        .size:           8
        .value_kind:     hidden_multigrid_sync_arg
      - .offset:         512
        .size:           4
        .value_kind:     hidden_dynamic_lds_size
    .group_segment_fixed_size: 0
    .kernarg_segment_align: 8
    .kernarg_segment_size: 648
    .language:       OpenCL C
    .language_version:
      - 2
      - 0
    .max_flat_workgroup_size: 512
    .name:           _Z14fwd_megakernel6Params
    .private_segment_fixed_size: 0
    .sgpr_count:     106
    .sgpr_spill_count: 62
    .symbol:         _Z14fwd_megakernel6Params.kd
    .uniform_work_group_size: 1
    .uses_dynamic_stack: false
    .vgpr_count:     256
    .vgpr_spill_count: 0
    .wavefront_size: 64
